# v71 + guard-banded T5 bias LUT in LDS (512 entries, edges replicated): near-tile bias block needs no per-element index clamps (146 -> 52 instructions)
# baseline (speedup 1.0000x reference)
.LBB0_1289:
	s_or_b64 exec, exec, s[8:9]
	s_xor_b64 s[4:5], s[12:13], -1
	s_and_b32 s69, s84, 1
	s_or_b64 s[4:5], s[2:3], s[4:5]
	s_and_b64 s[4:5], s[4:5], exec
	v_and_b32_e32 v148, 63, v18
	v_and_b32_e32 v162, 31, v18
	s_cselect_b32 s4, 0, s20
	v_lshrrev_b32_e32 v17, 5, v148
	v_or_b32_e32 v0, s4, v162
	s_lshl_b32 s8, s69, 7
	s_lshl_b32 s4, s69, 3
	s_waitcnt vmcnt(0)
	v_bitop3_b32 v2, s4, v4, v17 bitop3:0x36
	s_and_b64 s[4:5], exec, s[2:3]
	v_mul_lo_u32 v0, v0, s77
	s_cselect_b32 s76, s94, 0
	s_add_i32 s8, s8, 0
	v_lshlrev_b32_e32 v3, 4, v17
	v_add_u32_e32 v0, s8, v0
	s_mov_b32 s4, 0x18400
	s_waitcnt vmcnt(0) lgkmcnt(0)
	s_barrier
	v_add_u32_e32 v96, 0xffffff80, v160
	v_max_i32_e32 v96, 0, v96
	v_min_i32_e32 v96, 0xbf, v96
	v_lshlrev_b32_e32 v96, 2, v96
	v_add_u32_e32 v96, 0x20c00, v96
	ds_read_b32 v97, v96
	v_lshlrev_b32_e32 v98, 2, v160
	v_add_u32_e32 v98, 0x21000, v98
	s_waitcnt lgkmcnt(0)
	ds_write_b32 v98, v97
	s_waitcnt lgkmcnt(0)
	s_barrier
	v_add3_u32 v0, v0, v3, s4
	ds_read_b128 v[132:135], v0
	ds_read_b128 v[136:139], v0 offset:32
	ds_read_b128 v[140:143], v0 offset:64
	ds_read_b128 v[144:147], v0 offset:96
	s_cmp_gt_i32 s86, 0
	s_cselect_b64 s[4:5], -1, 0
	s_cmp_eq_u32 s76, 0
	s_cselect_b64 s[8:9], -1, 0
	s_and_b64 s[8:9], s[4:5], s[8:9]
	v_lshlrev_b32_e32 v2, 4, v2
	v_lshlrev_b32_e32 v4, 8, v162
	v_cndmask_b32_e64 v0, 0, 1, s[8:9]
	s_andn2_b64 vcc, exec, s[8:9]
	s_movk_i32 s8, 0x60
	v_lshlrev_b32_e32 v19, 3, v5
	v_or_b32_e32 v163, v2, v4
	v_bitop3_b32 v164, v2, 32, v4 bitop3:0x36
	v_bitop3_b32 v165, v2, 64, v4 bitop3:0x36
	v_cmp_ne_u32_e64 s[4:5], 1, v0
	v_bitop3_b32 v166, v2, s8, v4 bitop3:0x36
	s_cbranch_vccnz .LBB0_1291
	v_add_u32_e32 v0, 0, v163
	ds_read_b128 v[2:5], v0
	ds_read_b128 v[6:9], v0 offset:8192
	v_add_u32_e32 v0, 0, v164
	s_waitcnt lgkmcnt(1)
	v_mfma_f32_32x32x16_bf16 v[96:111], v[2:5], v[132:135], 0
	s_waitcnt lgkmcnt(0)
	v_mfma_f32_32x32x16_bf16 v[112:127], v[6:9], v[132:135], 0
	ds_read_b128 v[2:5], v0
	ds_read_b128 v[6:9], v0 offset:8192
	v_add_u32_e32 v0, 0, v165
	s_waitcnt lgkmcnt(1)
	v_mfma_f32_32x32x16_bf16 v[96:111], v[2:5], v[136:139], v[96:111]
	s_waitcnt lgkmcnt(0)
	v_mfma_f32_32x32x16_bf16 v[112:127], v[6:9], v[136:139], v[112:127]
	ds_read_b128 v[2:5], v0
	ds_read_b128 v[6:9], v0 offset:8192
	v_add_u32_e32 v0, 0, v166
	s_waitcnt lgkmcnt(1)
	v_mfma_f32_32x32x16_bf16 v[96:111], v[2:5], v[140:143], v[96:111]
	s_waitcnt lgkmcnt(0)
	v_mfma_f32_32x32x16_bf16 v[112:127], v[6:9], v[140:143], v[112:127]
	ds_read_b128 v[2:5], v0
	ds_read_b128 v[6:9], v0 offset:8192
	s_waitcnt lgkmcnt(1)
	v_mfma_f32_32x32x16_bf16 v[96:111], v[2:5], v[144:147], v[96:111]
	s_waitcnt lgkmcnt(0)
	v_mfma_f32_32x32x16_bf16 v[112:127], v[6:9], v[144:147], v[112:127]
	s_branch .LBB0_1292

.LBB0_1311:
	s_cmpk_gt_i32 s93, 0x7f
	s_cbranch_scc1 .LBB0_1313
	v_lshlrev_b32_e32 v218, 2, v179
	v_add_u32_e32 v218, 0x21180, v218
	ds_read_b32 v180, v218
	ds_read_b32 v181, v218 offset:4
	ds_read_b32 v188, v218 offset:8
	ds_read_b32 v189, v218 offset:12
	ds_read_b32 v190, v218 offset:32
	ds_read_b32 v191, v218 offset:36
	ds_read_b32 v192, v218 offset:40
	ds_read_b32 v193, v218 offset:44
	ds_read_b32 v194, v218 offset:64
	ds_read_b32 v195, v218 offset:68
	ds_read_b32 v196, v218 offset:72
	ds_read_b32 v197, v218 offset:76
	ds_read_b32 v198, v218 offset:96
	ds_read_b32 v199, v218 offset:100
	ds_read_b32 v200, v218 offset:104
	ds_read_b32 v201, v218 offset:108
	s_waitcnt lgkmcnt(0)
	ds_read_b32 v210, v218 offset:128
	ds_read_b32 v211, v218 offset:132
	ds_read_b32 v212, v218 offset:136
	ds_read_b32 v213, v218 offset:140
	ds_read_b32 v214, v218 offset:160
	ds_read_b32 v215, v218 offset:164
	ds_read_b32 v216, v218 offset:168
	ds_read_b32 v217, v218 offset:172
	ds_read_b32 v202, v218 offset:192
	ds_read_b32 v203, v218 offset:196
	ds_read_b32 v204, v218 offset:200
	ds_read_b32 v205, v218 offset:204
	ds_read_b32 v206, v218 offset:224
	ds_read_b32 v207, v218 offset:228
	ds_read_b32 v208, v218 offset:232
	ds_read_b32 v209, v218 offset:236
	v_pk_add_f32 v[96:97], v[96:97], v[180:181]
	v_pk_add_f32 v[98:99], v[98:99], v[188:189]
	v_pk_add_f32 v[100:101], v[100:101], v[190:191]
	v_pk_add_f32 v[102:103], v[102:103], v[192:193]
	v_pk_add_f32 v[104:105], v[104:105], v[194:195]
	v_pk_add_f32 v[106:107], v[106:107], v[196:197]
	v_pk_add_f32 v[108:109], v[108:109], v[198:199]
	v_pk_add_f32 v[110:111], v[110:111], v[200:201]
	s_waitcnt lgkmcnt(0)
	v_pk_add_f32 v[112:113], v[112:113], v[210:211]
	v_pk_add_f32 v[114:115], v[114:115], v[212:213]
	v_pk_add_f32 v[116:117], v[116:117], v[214:215]
	v_pk_add_f32 v[118:119], v[118:119], v[216:217]
	v_pk_add_f32 v[120:121], v[120:121], v[202:203]
	v_pk_add_f32 v[122:123], v[122:123], v[204:205]
	v_pk_add_f32 v[124:125], v[124:125], v[206:207]
	v_pk_add_f32 v[126:127], v[126:127], v[208:209]
